# stack6 variant: LDS-DMA issue moved to the very start of the step (two V pieces before the first QK MFMA, rest right after)
# speedup vs baseline: 1.0190x; 1.0190x over previous
.Li0_entry:
	v_add_u32_e32 v167, s79, v147
	v_add_u32_e32 v227, s79, v149
	v_add_u32_e32 v194, s79, v151
	v_add_u32_e32 v195, s79, v153
	ds_read_b128 v[64:67], v167
	ds_read_b128 v[188:191], v227
	ds_read_b128 v[228:231], v194
	s_mov_b64 s[54:55], 0xe404000
	s_add_i32 m0, s96, 0x8000
	v_lshl_add_u64 v[192:193], v[134:135], 0, s[54:55]
	s_nop 0
	global_load_lds_dwordx4 v[192:193], off
	s_mov_b64 s[54:55], 0xe406000
	s_add_i32 m0, s96, 0xa000
	v_lshl_add_u64 v[192:193], v[134:135], 0, s[54:55]
	s_nop 0
	global_load_lds_dwordx4 v[192:193], off
	s_waitcnt lgkmcnt(2)
	v_mfma_f32_32x32x16_bf16 v[64:79], v[64:67], v[80:83], 0
	s_waitcnt lgkmcnt(1)
	v_mfma_f32_32x32x16_bf16 v[64:79], v[188:191], v[84:87], v[64:79]
	ds_read_b128 v[188:191], v195
	s_mov_b64 s[54:55], 0xe804000
	s_add_i32 m0, s96, 0xc000
	v_lshl_add_u64 v[192:193], v[134:135], 0, s[54:55]
	s_nop 0
	global_load_lds_dwordx4 v[192:193], off
	v_cndmask_b32_e64 v173, v113, v121, s[2:3]
	v_cndmask_b32_e64 v172, v112, v120, s[2:3]
	v_cndmask_b32_e64 v177, v121, v113, s[2:3]
	v_cndmask_b32_e64 v176, v120, v112, s[2:3]
	s_waitcnt lgkmcnt(1)
	v_mfma_f32_32x32x16_bf16 v[64:79], v[228:231], v[88:91], v[64:79]
	ds_read_b128 v[228:231], v167 offset:128
	s_mov_b64 s[54:55], 0xe806000
	s_add_i32 m0, s96, 0xe000
	v_lshl_add_u64 v[192:193], v[134:135], 0, s[54:55]
	s_nop 0
	global_load_lds_dwordx4 v[192:193], off
	v_cndmask_b32_e64 v171, v119, v127, s[2:3]
	v_cndmask_b32_e64 v170, v118, v126, s[2:3]
	v_cndmask_b32_e64 v169, v117, v125, s[2:3]
	v_cndmask_b32_e64 v168, v116, v124, s[2:3]
	s_waitcnt lgkmcnt(1)
	v_mfma_f32_32x32x16_bf16 v[64:79], v[188:191], v[92:95], v[64:79]
	ds_read_b128 v[188:191], v227 offset:128
	s_cmp_gt_i32 s19, s18
	s_cbranch_scc1 .Li0_kskip
	v_lshl_add_u64 v[192:193], s[50:51], 0, v[130:131]
	s_mov_b64 s[54:55], 0xc408000
	s_mov_b32 m0, s97
	v_lshl_add_u64 v[192:193], v[192:193], 0, s[54:55]
	s_nop 0
	global_load_lds_dwordx4 v[192:193], off
	v_lshl_add_u64 v[192:193], s[50:51], 0, v[130:131]
	s_mov_b64 s[54:55], 0xc40a000
	s_mov_b32 m0, s26
	v_lshl_add_u64 v[192:193], v[192:193], 0, s[54:55]
	s_nop 0
	global_load_lds_dwordx4 v[192:193], off
.Li0_kskip:
	v_cndmask_b32_e64 v175, v115, v123, s[2:3]
	v_cndmask_b32_e64 v174, v114, v122, s[2:3]
	v_cndmask_b32_e64 v127, v127, v119, s[2:3]
	v_cndmask_b32_e64 v126, v126, v118, s[2:3]
	s_waitcnt lgkmcnt(1)
	v_mfma_f32_32x32x16_bf16 v[64:79], v[228:231], v[96:99], v[64:79]
	ds_read_b128 v[228:231], v194 offset:128
	v_cndmask_b32_e64 v125, v125, v117, s[2:3]
	v_cndmask_b32_e64 v124, v124, v116, s[2:3]
	v_cndmask_b32_e64 v179, v123, v115, s[2:3]
	v_cndmask_b32_e64 v178, v122, v114, s[2:3]
	s_waitcnt lgkmcnt(1)
	v_mfma_f32_32x32x16_bf16 v[64:79], v[188:191], v[100:103], v[64:79]
	ds_read_b128 v[188:191], v195 offset:128
	ds_read_b64_tr_b16 v[180:181], v158 offset:0
	ds_read_b64_tr_b16 v[182:183], v158 offset:0x800
	ds_read_b64_tr_b16 v[184:185], v158 offset:0x1000
	ds_read_b64_tr_b16 v[186:187], v158 offset:0x1800
	s_waitcnt lgkmcnt(5)
	v_mfma_f32_32x32x16_bf16 v[64:79], v[228:231], v[104:107], v[64:79]
	v_max_f32_e32 v194, v166, v166
	v_max_f32_e32 v195, v164, v164
	v_max_f32_e32 v194, v195, v194
	v_sub_f32_e32 v195, v194, v165
	v_mul_f32_e32 v195, 0x3db504f3, v195
	v_cmp_ge_f32_e32 vcc, s88, v195
	s_waitcnt lgkmcnt(4)
	v_mfma_f32_32x32x16_bf16 v[64:79], v[188:191], v[108:111], v[64:79]
	s_cmp_eq_u64 vcc, exec
	s_cbranch_scc0 .Li0_fb
	v_mov_b32_e32 v166, v165
	s_sub_i32 s52, s83, 64
	s_cmp_le_i32 s52, s25
	s_cbranch_scc1 .Li0_sm
	s_nop 7
	v_add_u32_e32 v112, 0x5b, v162
	v_cmp_gt_u32_e32 vcc, s86, v112
	v_add_u32_e32 v112, s83, v163
	v_add_u32_e32 v112, 0xffffffa1, v112
	v_cndmask_b32_e32 v64, v141, v64, vcc
	v_cmp_lt_u32_e32 vcc, s87, v112
	v_add_u32_e32 v112, 0x59, v162
	s_nop 0
	v_cndmask_b32_e32 v65, v141, v65, vcc
	v_cmp_gt_u32_e32 vcc, s86, v112
	v_add_u32_e32 v112, 0x58, v162
	s_nop 0
	v_cndmask_b32_e32 v66, v141, v66, vcc
	v_cmp_gt_u32_e32 vcc, s86, v112
	v_add_u32_e32 v112, 0x53, v162
	s_nop 0
	v_cndmask_b32_e32 v67, v141, v67, vcc
	v_cmp_gt_u32_e32 vcc, s86, v112
	v_add_u32_e32 v112, 0x52, v162
	s_nop 0
	v_cndmask_b32_e32 v68, v141, v68, vcc
	v_cmp_gt_u32_e32 vcc, s86, v112
	v_add_u32_e32 v112, 0x51, v162
	s_nop 0
	v_cndmask_b32_e32 v69, v141, v69, vcc
	v_cmp_gt_u32_e32 vcc, s86, v112
	v_add_u32_e32 v112, 0x50, v162
	s_nop 0
	v_cndmask_b32_e32 v70, v141, v70, vcc
	v_cmp_gt_u32_e32 vcc, s86, v112
	v_add_u32_e32 v112, 0x4b, v162
	s_nop 0
	v_cndmask_b32_e32 v71, v141, v71, vcc
	v_cmp_gt_u32_e32 vcc, s86, v112
	v_add_u32_e32 v112, 0x4a, v162
	s_nop 0
	v_cndmask_b32_e32 v72, v141, v72, vcc
	v_cmp_gt_u32_e32 vcc, s86, v112
	v_add_u32_e32 v112, 0x49, v162
	s_nop 0
	v_cndmask_b32_e32 v73, v141, v73, vcc
	v_cmp_gt_u32_e32 vcc, s86, v112
	v_add_u32_e32 v112, 0x48, v162
	s_nop 0
	v_cndmask_b32_e32 v74, v141, v74, vcc
	v_cmp_gt_u32_e32 vcc, s86, v112
	v_add_u32_e32 v112, 0x43, v162
	s_nop 0
	v_cndmask_b32_e32 v75, v141, v75, vcc
	v_cmp_gt_u32_e32 vcc, s86, v112
	v_add_u32_e32 v112, 0x42, v162
	s_nop 0
	v_cndmask_b32_e32 v76, v141, v76, vcc
	v_cmp_gt_u32_e32 vcc, s86, v112
	v_add_u32_e32 v112, 0x41, v162
	s_nop 0
	v_cndmask_b32_e32 v77, v141, v77, vcc
	v_cmp_gt_u32_e32 vcc, s86, v112
	v_add_u32_e32 v112, 64, v162
	s_nop 0
	v_cndmask_b32_e32 v78, v141, v78, vcc
	v_cmp_gt_u32_e32 vcc, s86, v112
	s_nop 1
	v_cndmask_b32_e32 v79, v141, v79, vcc

.Li1_entry:
	ds_read_b128 v[64:67], v148
	ds_read_b128 v[188:191], v150
	ds_read_b128 v[228:231], v152
	s_mov_b64 s[56:57], 0xe408000
	s_mov_b32 m0, s96
	v_lshl_add_u64 v[192:193], v[134:135], 0, s[56:57]
	s_nop 0
	global_load_lds_dwordx4 v[192:193], off
	s_mov_b64 s[56:57], 0xe40a000
	s_mov_b32 m0, s6
	v_lshl_add_u64 v[192:193], v[134:135], 0, s[56:57]
	s_nop 0
	global_load_lds_dwordx4 v[192:193], off
	s_waitcnt lgkmcnt(2)
	v_mfma_f32_32x32x16_bf16 v[64:79], v[64:67], v[80:83], 0
	s_waitcnt lgkmcnt(1)
	v_mfma_f32_32x32x16_bf16 v[64:79], v[188:191], v[84:87], v[64:79]
	ds_read_b128 v[188:191], v154
	s_mov_b64 s[56:57], 0xe808000
	s_mov_b32 m0, s7
	v_lshl_add_u64 v[192:193], v[134:135], 0, s[56:57]
	s_nop 0
	global_load_lds_dwordx4 v[192:193], off
	v_cndmask_b32_e64 v173, v113, v121, s[2:3]
	v_cndmask_b32_e64 v172, v112, v120, s[2:3]
	v_cndmask_b32_e64 v177, v121, v113, s[2:3]
	v_cndmask_b32_e64 v176, v120, v112, s[2:3]
	s_waitcnt lgkmcnt(1)
	v_mfma_f32_32x32x16_bf16 v[64:79], v[228:231], v[88:91], v[64:79]
	ds_read_b128 v[228:231], v148 offset:128
	s_mov_b64 s[56:57], 0xe80a000
	s_mov_b32 m0, s24
	v_lshl_add_u64 v[192:193], v[134:135], 0, s[56:57]
	s_nop 0
	global_load_lds_dwordx4 v[192:193], off
	v_cndmask_b32_e64 v171, v127, v119, s[2:3]
	v_cndmask_b32_e64 v170, v126, v118, s[2:3]
	v_cndmask_b32_e64 v169, v125, v117, s[2:3]
	v_cndmask_b32_e64 v168, v124, v116, s[2:3]
	s_waitcnt lgkmcnt(1)
	v_mfma_f32_32x32x16_bf16 v[64:79], v[188:191], v[92:95], v[64:79]
	ds_read_b128 v[188:191], v150 offset:128
	s_add_i32 s56, s19, 1
	s_cmp_gt_i32 s56, s18
	s_cbranch_scc1 .Li1_kskip
	v_lshl_add_u64 v[192:193], s[50:51], 0, v[130:131]
	s_mov_b64 s[56:57], 0xc40c000
	s_mov_b32 m0, s27
	v_lshl_add_u64 v[192:193], v[192:193], 0, s[56:57]
	s_nop 0
	global_load_lds_dwordx4 v[192:193], off
	v_lshl_add_u64 v[192:193], s[50:51], 0, v[130:131]
	s_mov_b64 s[56:57], 0xc40e000
	s_mov_b32 m0, s62
	v_lshl_add_u64 v[192:193], v[192:193], 0, s[56:57]
	s_nop 0
	global_load_lds_dwordx4 v[192:193], off
.Li1_kskip:
	v_cndmask_b32_e64 v175, v115, v123, s[2:3]
	v_cndmask_b32_e64 v174, v114, v122, s[2:3]
	v_cndmask_b32_e64 v127, v119, v127, s[2:3]
	v_cndmask_b32_e64 v126, v118, v126, s[2:3]
	s_waitcnt lgkmcnt(1)
	v_mfma_f32_32x32x16_bf16 v[64:79], v[228:231], v[96:99], v[64:79]
	ds_read_b128 v[228:231], v152 offset:128
	v_cndmask_b32_e64 v125, v117, v125, s[2:3]
	v_cndmask_b32_e64 v124, v116, v124, s[2:3]
	v_cndmask_b32_e64 v179, v123, v115, s[2:3]
	v_cndmask_b32_e64 v178, v122, v114, s[2:3]
	s_waitcnt lgkmcnt(1)
	v_mfma_f32_32x32x16_bf16 v[64:79], v[188:191], v[100:103], v[64:79]
	ds_read_b128 v[188:191], v154 offset:128
	ds_read_b64_tr_b16 v[180:181], v158 offset:0x8000
	ds_read_b64_tr_b16 v[182:183], v158 offset:0x8800
	ds_read_b64_tr_b16 v[184:185], v158 offset:0x9000
	ds_read_b64_tr_b16 v[186:187], v158 offset:0x9800
	s_waitcnt lgkmcnt(5)
	v_mfma_f32_32x32x16_bf16 v[64:79], v[228:231], v[104:107], v[64:79]
	v_max_f32_e32 v194, v128, v128
	v_max_f32_e32 v195, v164, v164
	v_max_f32_e32 v194, v195, v194
	v_sub_f32_e32 v195, v194, v166
	v_mul_f32_e32 v195, 0x3db504f3, v195
	v_cmp_ge_f32_e32 vcc, s88, v195
	s_waitcnt lgkmcnt(4)
	v_mfma_f32_32x32x16_bf16 v[64:79], v[188:191], v[108:111], v[64:79]
	s_cmp_eq_u64 vcc, exec
	s_cbranch_scc0 .Li1_fb
	v_mov_b32_e32 v165, v166
	s_cmp_le_i32 s83, s25
	s_cbranch_scc1 .Li1_sm
	s_nop 7
	v_add_u32_e32 v112, 27, v162
	v_cmp_gt_u32_e32 vcc, s86, v112
	v_add_u32_e32 v112, s83, v163
	v_subrev_u32_e32 v112, 31, v112
	v_cndmask_b32_e32 v64, v141, v64, vcc
	v_cmp_lt_u32_e32 vcc, s87, v112
	v_add_u32_e32 v112, 25, v162
	s_nop 0
	v_cndmask_b32_e32 v65, v141, v65, vcc
	v_cmp_gt_u32_e32 vcc, s86, v112
	v_add_u32_e32 v112, 24, v162
	s_nop 0
	v_cndmask_b32_e32 v66, v141, v66, vcc
	v_cmp_gt_u32_e32 vcc, s86, v112
	v_add_u32_e32 v112, 19, v162
	s_nop 0
	v_cndmask_b32_e32 v67, v141, v67, vcc
	v_cmp_gt_u32_e32 vcc, s86, v112
	v_add_u32_e32 v112, 18, v162
	s_nop 0
	v_cndmask_b32_e32 v68, v141, v68, vcc
	v_cmp_gt_u32_e32 vcc, s86, v112
	v_add_u32_e32 v112, 17, v162
	s_nop 0
	v_cndmask_b32_e32 v69, v141, v69, vcc
	v_cmp_gt_u32_e32 vcc, s86, v112
	v_add_u32_e32 v112, 16, v162
	s_nop 0
	v_cndmask_b32_e32 v70, v141, v70, vcc
	v_cmp_gt_u32_e32 vcc, s86, v112
	v_add_u32_e32 v112, 11, v162
	s_nop 0
	v_cndmask_b32_e32 v71, v141, v71, vcc
	v_cmp_gt_u32_e32 vcc, s86, v112
	v_add_u32_e32 v112, 10, v162
	s_nop 0
	v_cndmask_b32_e32 v72, v141, v72, vcc
	v_cmp_gt_u32_e32 vcc, s86, v112
	v_add_u32_e32 v112, 9, v162
	s_nop 0
	v_cndmask_b32_e32 v73, v141, v73, vcc
	v_cmp_gt_u32_e32 vcc, s86, v112
	v_add_u32_e32 v112, 8, v162
	s_nop 0
	v_cndmask_b32_e32 v74, v141, v74, vcc
	v_cmp_gt_u32_e32 vcc, s86, v112
	v_add_u32_e32 v112, 3, v162
	s_nop 0
	v_cndmask_b32_e32 v75, v141, v75, vcc
	v_cmp_gt_u32_e32 vcc, s86, v112
	v_add_u32_e32 v112, 2, v162
	s_nop 0
	v_cndmask_b32_e32 v76, v141, v76, vcc
	v_cmp_gt_u32_e32 vcc, s86, v112
	v_add_u32_e32 v112, 1, v162
	s_nop 0
	v_cndmask_b32_e32 v77, v141, v77, vcc
	v_cmp_gt_u32_e32 vcc, s86, v112
	s_nop 1
	v_cndmask_b32_e32 v78, v141, v78, vcc
	v_cmp_gt_u32_e32 vcc, s86, v162
	s_nop 1
	v_cndmask_b32_e32 v79, v141, v79, vcc
